# mixer-GEMM tail weight copies (W2in, Wout on the 60 idle workgroups) replaced by the hand-written quad-item copy routine
# speedup vs baseline: 1.0103x; 1.0103x over previous
.LBB0_700:
	v_readlane_b32 s4, v246, 17
	s_cmpk_lt_i32 s96, 0xc4
	v_readlane_b32 s5, v246, 18
	s_cselect_b64 s[2:3], -1, 0
	s_xor_b64 s[4:5], s[4:5], -1
	s_or_b64 s[2:3], s[2:3], s[4:5]
	s_and_b64 vcc, exec, s[2:3]
	s_cbranch_vccnz .LBB0_713
	v_lshrrev_b32_e32 v1, 6, v236
	v_and_b32_e32 v2, 63, v236
	v_readfirstlane_b32 s25, v1
	v_and_b32_e32 v3, 31, v2
	v_lshrrev_b32_e32 v4, 5, v2
	s_nop 3
	s_lshl_b32 s2, s25, 14
	v_bfe_u32 v5, v3, 2, 1
	v_xor_b32_e32 v5, v5, v4
	v_lshlrev_b32_e32 v5, 6, v5
	v_lshl_or_b32 v5, v3, 9, v5
	v_add_u32_e32 v5, s2, v5
	v_and_b32_e32 v6, 3, v3
	v_xor_b32_e32 v7, 0, v6
	v_lshl_add_u32 v7, v7, 4, v5
	v_xor_b32_e32 v8, 1, v6
	v_lshl_add_u32 v8, v8, 4, v5
	v_xor_b32_e32 v9, 2, v6
	v_lshl_add_u32 v9, v9, 4, v5
	v_xor_b32_e32 v10, 3, v6
	v_lshl_add_u32 v10, v10, 4, v5
	v_and_b32_e32 v11, 7, v2
	v_xor_b32_e32 v11, v11, v4
	v_lshrrev_b32_e32 v12, 3, v2
	v_lshlrev_b32_e32 v12, 7, v12
	v_add_u32_e32 v12, s2, v12
	v_xor_b32_e32 v13, 0, v11
	v_lshl_add_u32 v13, v13, 4, v12
	v_xor_b32_e32 v14, 2, v11
	v_lshl_add_u32 v14, v14, 4, v12
	v_xor_b32_e32 v15, 4, v11
	v_lshl_add_u32 v15, v15, 4, v12
	v_xor_b32_e32 v16, 6, v11
	v_lshl_add_u32 v16, v16, 4, v12
	v_lshrrev_b32_e32 v17, 3, v2
	v_lshlrev_b32_e32 v17, 11, v17
	v_and_b32_e32 v18, 7, v2
	v_lshl_or_b32 v17, v18, 4, v17
	s_sub_i32 s26, s96, 0xc4
	s_lshl_b32 s26, s26, 3
	s_add_i32 s26, s26, s25
	s_mov_b32 s3, 0
.Lp5w_round:
	s_cmpk_ge_u32 s26, 0x340
	s_cbranch_scc1 .Lp5w_done
	s_movk_i32 s9, 0x80
	s_cmpk_lt_u32 s26, 0x2c0
	s_cbranch_scc0 .Lp5w_wout
	s_mul_i32 s4, s26, 0x5d2
	s_lshr_b32 s4, s4, 16
	s_mul_i32 s5, s4, 44
	s_sub_i32 s5, s26, s5
	s_and_b32 s6, s5, 1
	s_mul_i32 s6, s6, 0xb00
	s_lshr_b32 s7, s5, 1
	s_lshl_b32 s7, s7, 7
	s_add_i32 s6, s6, s7
	s_movk_i32 s8, 0x1600
	s_mov_b32 s18, s66
	s_mov_b32 s19, s67
	s_add_u32 s12, s74, 0x2500000
	s_addc_u32 s13, s75, 0
	s_branch .Lp5w_go
.Lp5w_wout:
	s_sub_i32 s14, s26, 0x2c0
	s_lshr_b32 s4, s14, 3
	s_and_b32 s5, s14, 7
	s_lshl_b32 s6, s5, 7
	s_movk_i32 s8, 0x400
	s_mov_b32 s18, s62
	s_mov_b32 s19, s63
	s_add_u32 s12, s74, 0x2300000
	s_addc_u32 s13, s75, 0

.Lp5w_nozero:
	s_mov_b64 s[20:21], exec
	v_cmp_gt_u32_e32 vcc, s17, v3
	s_and_b64 exec, exec, vcc
	global_load_dwordx4 v[20:23], v19, s[18:19] nt
	s_add_u32 s18, s18, s15
	s_addc_u32 s19, s19, 0
	global_load_dwordx4 v[24:27], v19, s[18:19] nt
	s_add_u32 s18, s18, s15
	s_addc_u32 s19, s19, 0
	global_load_dwordx4 v[28:31], v19, s[18:19] nt
	s_add_u32 s18, s18, s15
	s_addc_u32 s19, s19, 0
	global_load_dwordx4 v[32:35], v19, s[18:19] nt
	s_add_u32 s18, s18, s15
	s_addc_u32 s19, s19, 0
	global_load_dwordx4 v[36:39], v19, s[18:19] nt
	s_add_u32 s18, s18, s15
	s_addc_u32 s19, s19, 0
	global_load_dwordx4 v[40:43], v19, s[18:19] nt
	s_add_u32 s18, s18, s15
	s_addc_u32 s19, s19, 0
	global_load_dwordx4 v[44:47], v19, s[18:19] nt
	s_add_u32 s18, s18, s15
	s_addc_u32 s19, s19, 0
	global_load_dwordx4 v[48:51], v19, s[18:19] nt
	s_add_u32 s18, s18, s15
	s_addc_u32 s19, s19, 0
	global_load_dwordx4 v[52:55], v19, s[18:19] nt
	s_add_u32 s18, s18, s15
	s_addc_u32 s19, s19, 0
	global_load_dwordx4 v[56:59], v19, s[18:19] nt
	s_add_u32 s18, s18, s15
	s_addc_u32 s19, s19, 0
	global_load_dwordx4 v[60:63], v19, s[18:19] nt
	s_add_u32 s18, s18, s15
	s_addc_u32 s19, s19, 0
	global_load_dwordx4 v[64:67], v19, s[18:19] nt
	s_add_u32 s18, s18, s15
	s_addc_u32 s19, s19, 0
	global_load_dwordx4 v[68:71], v19, s[18:19] nt
	s_add_u32 s18, s18, s15
	s_addc_u32 s19, s19, 0
	global_load_dwordx4 v[76:79], v19, s[18:19] nt
	s_add_u32 s18, s18, s15
	s_addc_u32 s19, s19, 0
	global_load_dwordx4 v[80:83], v19, s[18:19] nt
	s_add_u32 s18, s18, s15
	s_addc_u32 s19, s19, 0
	global_load_dwordx4 v[84:87], v19, s[18:19] nt
	s_add_u32 s18, s18, s15
	s_addc_u32 s19, s19, 0
	global_load_dwordx4 v[88:91], v19, s[18:19] nt
	s_add_u32 s18, s18, s15
	s_addc_u32 s19, s19, 0
	global_load_dwordx4 v[92:95], v19, s[18:19] nt
	s_add_u32 s18, s18, s15
	s_addc_u32 s19, s19, 0
	global_load_dwordx4 v[108:111], v19, s[18:19] nt
	s_add_u32 s18, s18, s15
	s_addc_u32 s19, s19, 0
	global_load_dwordx4 v[112:115], v19, s[18:19] nt
	s_add_u32 s18, s18, s15
	s_addc_u32 s19, s19, 0
	global_load_dwordx4 v[116:119], v19, s[18:19] nt
	s_add_u32 s18, s18, s15
	s_addc_u32 s19, s19, 0
	global_load_dwordx4 v[120:123], v19, s[18:19] nt
	s_add_u32 s18, s18, s15
	s_addc_u32 s19, s19, 0
	global_load_dwordx4 v[124:127], v19, s[18:19] nt
	s_add_u32 s18, s18, s15
	s_addc_u32 s19, s19, 0
	global_load_dwordx4 v[128:131], v19, s[18:19] nt
	s_add_u32 s18, s18, s15
	s_addc_u32 s19, s19, 0
	global_load_dwordx4 v[132:135], v19, s[18:19] nt
	s_add_u32 s18, s18, s15
	s_addc_u32 s19, s19, 0
	global_load_dwordx4 v[136:139], v19, s[18:19] nt
	s_add_u32 s18, s18, s15
	s_addc_u32 s19, s19, 0
	global_load_dwordx4 v[140:143], v19, s[18:19] nt
	s_add_u32 s18, s18, s15
	s_addc_u32 s19, s19, 0
	global_load_dwordx4 v[144:147], v19, s[18:19] nt
	s_add_u32 s18, s18, s15
	s_addc_u32 s19, s19, 0
	global_load_dwordx4 v[148:151], v19, s[18:19] nt
	s_add_u32 s18, s18, s15
	s_addc_u32 s19, s19, 0
	global_load_dwordx4 v[152:155], v19, s[18:19] nt
	s_add_u32 s18, s18, s15
	s_addc_u32 s19, s19, 0
	global_load_dwordx4 v[156:159], v19, s[18:19] nt
	s_add_u32 s18, s18, s15
	s_addc_u32 s19, s19, 0
	global_load_dwordx4 v[160:163], v19, s[18:19] nt
	s_mov_b64 exec, s[20:21]
	s_lshl_b32 s14, s5, 18
	s_lshl_b32 s22, s4, 7
	s_add_i32 s14, s14, s22
	s_add_u32 s22, s12, s14
	s_addc_u32 s23, s13, 0
	s_waitcnt vmcnt(0)
	v_cvt_pk_bf16_f32 v20, v20, v24
	v_cvt_pk_bf16_f32 v21, v21, v25
	v_cvt_pk_bf16_f32 v22, v22, v26
	v_cvt_pk_bf16_f32 v23, v23, v27
	v_cvt_pk_bf16_f32 v28, v28, v32
	v_cvt_pk_bf16_f32 v29, v29, v33
	v_cvt_pk_bf16_f32 v30, v30, v34
	v_cvt_pk_bf16_f32 v31, v31, v35
	v_cvt_pk_bf16_f32 v36, v36, v40
	v_cvt_pk_bf16_f32 v37, v37, v41
	v_cvt_pk_bf16_f32 v38, v38, v42
	v_cvt_pk_bf16_f32 v39, v39, v43
	v_cvt_pk_bf16_f32 v44, v44, v48
	v_cvt_pk_bf16_f32 v45, v45, v49
	v_cvt_pk_bf16_f32 v46, v46, v50
	v_cvt_pk_bf16_f32 v47, v47, v51
	v_cvt_pk_bf16_f32 v52, v52, v56
	v_cvt_pk_bf16_f32 v53, v53, v57
	v_cvt_pk_bf16_f32 v54, v54, v58
	v_cvt_pk_bf16_f32 v55, v55, v59
	v_cvt_pk_bf16_f32 v60, v60, v64
	v_cvt_pk_bf16_f32 v61, v61, v65
	v_cvt_pk_bf16_f32 v62, v62, v66
	v_cvt_pk_bf16_f32 v63, v63, v67
	v_cvt_pk_bf16_f32 v68, v68, v76
	v_cvt_pk_bf16_f32 v69, v69, v77
	v_cvt_pk_bf16_f32 v70, v70, v78
	v_cvt_pk_bf16_f32 v71, v71, v79
	v_cvt_pk_bf16_f32 v80, v80, v84
	v_cvt_pk_bf16_f32 v81, v81, v85
	v_cvt_pk_bf16_f32 v82, v82, v86
	v_cvt_pk_bf16_f32 v83, v83, v87
	v_cvt_pk_bf16_f32 v88, v88, v92
	v_cvt_pk_bf16_f32 v89, v89, v93
	v_cvt_pk_bf16_f32 v90, v90, v94
	v_cvt_pk_bf16_f32 v91, v91, v95
	v_cvt_pk_bf16_f32 v108, v108, v112
	v_cvt_pk_bf16_f32 v109, v109, v113
	v_cvt_pk_bf16_f32 v110, v110, v114
	v_cvt_pk_bf16_f32 v111, v111, v115
	v_cvt_pk_bf16_f32 v116, v116, v120
	v_cvt_pk_bf16_f32 v117, v117, v121
	v_cvt_pk_bf16_f32 v118, v118, v122
	v_cvt_pk_bf16_f32 v119, v119, v123
	v_cvt_pk_bf16_f32 v124, v124, v128
	v_cvt_pk_bf16_f32 v125, v125, v129
	v_cvt_pk_bf16_f32 v126, v126, v130
	v_cvt_pk_bf16_f32 v127, v127, v131
	v_cvt_pk_bf16_f32 v132, v132, v136
	v_cvt_pk_bf16_f32 v133, v133, v137
	v_cvt_pk_bf16_f32 v134, v134, v138
	v_cvt_pk_bf16_f32 v135, v135, v139
	v_cvt_pk_bf16_f32 v140, v140, v144
	v_cvt_pk_bf16_f32 v141, v141, v145
	v_cvt_pk_bf16_f32 v142, v142, v146
	v_cvt_pk_bf16_f32 v143, v143, v147
	v_cvt_pk_bf16_f32 v148, v148, v152
	v_cvt_pk_bf16_f32 v149, v149, v153
	v_cvt_pk_bf16_f32 v150, v150, v154
	v_cvt_pk_bf16_f32 v151, v151, v155
	v_cvt_pk_bf16_f32 v156, v156, v160
	v_cvt_pk_bf16_f32 v157, v157, v161
	v_cvt_pk_bf16_f32 v158, v158, v162
	v_cvt_pk_bf16_f32 v159, v159, v163
	ds_write_b32 v7, v20
	ds_write_b32 v7, v21 offset:128
	ds_write_b32 v7, v22 offset:256
	ds_write_b32 v7, v23 offset:384
	ds_write_b32 v7, v28 offset:4
	ds_write_b32 v7, v29 offset:132
	ds_write_b32 v7, v30 offset:260
	ds_write_b32 v7, v31 offset:388
	ds_write_b32 v7, v36 offset:8
	ds_write_b32 v7, v37 offset:136
	ds_write_b32 v7, v38 offset:264
	ds_write_b32 v7, v39 offset:392
	ds_write_b32 v7, v44 offset:12
	ds_write_b32 v7, v45 offset:140
	ds_write_b32 v7, v46 offset:268
	ds_write_b32 v7, v47 offset:396
	ds_write_b32 v8, v52
	ds_write_b32 v8, v53 offset:128
	ds_write_b32 v8, v54 offset:256
	ds_write_b32 v8, v55 offset:384
	ds_write_b32 v8, v60 offset:4
	ds_write_b32 v8, v61 offset:132
	ds_write_b32 v8, v62 offset:260
	ds_write_b32 v8, v63 offset:388
	ds_write_b32 v8, v68 offset:8
	ds_write_b32 v8, v69 offset:136
	ds_write_b32 v8, v70 offset:264
	ds_write_b32 v8, v71 offset:392
	ds_write_b32 v8, v80 offset:12
	ds_write_b32 v8, v81 offset:140
	ds_write_b32 v8, v82 offset:268
	ds_write_b32 v8, v83 offset:396
	ds_write_b32 v9, v88
	ds_write_b32 v9, v89 offset:128
	ds_write_b32 v9, v90 offset:256
	ds_write_b32 v9, v91 offset:384
	ds_write_b32 v9, v108 offset:4
	ds_write_b32 v9, v109 offset:132
	ds_write_b32 v9, v110 offset:260
	ds_write_b32 v9, v111 offset:388
	ds_write_b32 v9, v116 offset:8
	ds_write_b32 v9, v117 offset:136
	ds_write_b32 v9, v118 offset:264
	ds_write_b32 v9, v119 offset:392
	ds_write_b32 v9, v124 offset:12
	ds_write_b32 v9, v125 offset:140
	ds_write_b32 v9, v126 offset:268
	ds_write_b32 v9, v127 offset:396
	ds_write_b32 v10, v132
	ds_write_b32 v10, v133 offset:128
	ds_write_b32 v10, v134 offset:256
	ds_write_b32 v10, v135 offset:384
	ds_write_b32 v10, v140 offset:4
	ds_write_b32 v10, v141 offset:132
	ds_write_b32 v10, v142 offset:260
	ds_write_b32 v10, v143 offset:388
	ds_write_b32 v10, v148 offset:8
	ds_write_b32 v10, v149 offset:136
	ds_write_b32 v10, v150 offset:264
	ds_write_b32 v10, v151 offset:392
	ds_write_b32 v10, v156 offset:12
	ds_write_b32 v10, v157 offset:140
	ds_write_b32 v10, v158 offset:268
	ds_write_b32 v10, v159 offset:396
	s_waitcnt lgkmcnt(0)
	ds_read_b128 v[24:27], v13
	ds_read_b128 v[32:35], v14 offset:1024
	ds_read_b128 v[40:43], v15 offset:2048
	ds_read_b128 v[48:51], v16 offset:3072
	ds_read_b128 v[56:59], v13 offset:4096
	ds_read_b128 v[64:67], v14 offset:5120
	ds_read_b128 v[76:79], v15 offset:6144
	ds_read_b128 v[84:87], v16 offset:7168
	ds_read_b128 v[92:95], v13 offset:8192
	ds_read_b128 v[112:115], v14 offset:9216
	ds_read_b128 v[120:123], v15 offset:10240
	ds_read_b128 v[128:131], v16 offset:11264
	ds_read_b128 v[136:139], v13 offset:12288
	ds_read_b128 v[144:147], v14 offset:13312
	ds_read_b128 v[152:155], v15 offset:14336
	ds_read_b128 v[160:163], v16 offset:15360
	s_waitcnt lgkmcnt(15)
	global_store_dwordx4 v17, v[24:27], s[22:23]
	s_add_u32 s22, s22, 0x4000
	s_addc_u32 s23, s23, 0
	s_waitcnt lgkmcnt(14)
	global_store_dwordx4 v17, v[32:35], s[22:23]
	s_add_u32 s22, s22, 0x4000
	s_addc_u32 s23, s23, 0
	s_waitcnt lgkmcnt(13)
	global_store_dwordx4 v17, v[40:43], s[22:23]
	s_add_u32 s22, s22, 0x4000
	s_addc_u32 s23, s23, 0
	s_waitcnt lgkmcnt(12)
	global_store_dwordx4 v17, v[48:51], s[22:23]
	s_add_u32 s22, s22, 0x4000
	s_addc_u32 s23, s23, 0
	s_waitcnt lgkmcnt(11)
	global_store_dwordx4 v17, v[56:59], s[22:23]
	s_add_u32 s22, s22, 0x4000
	s_addc_u32 s23, s23, 0
	s_waitcnt lgkmcnt(10)
	global_store_dwordx4 v17, v[64:67], s[22:23]
	s_add_u32 s22, s22, 0x4000
	s_addc_u32 s23, s23, 0
	s_waitcnt lgkmcnt(9)
	global_store_dwordx4 v17, v[76:79], s[22:23]
	s_add_u32 s22, s22, 0x4000
	s_addc_u32 s23, s23, 0
	s_waitcnt lgkmcnt(8)
	global_store_dwordx4 v17, v[84:87], s[22:23]
	s_add_u32 s22, s22, 0x4000
	s_addc_u32 s23, s23, 0
	s_waitcnt lgkmcnt(7)
	global_store_dwordx4 v17, v[92:95], s[22:23]
	s_add_u32 s22, s22, 0x4000
	s_addc_u32 s23, s23, 0
	s_waitcnt lgkmcnt(6)
	global_store_dwordx4 v17, v[112:115], s[22:23]
	s_add_u32 s22, s22, 0x4000
	s_addc_u32 s23, s23, 0
	s_waitcnt lgkmcnt(5)
	global_store_dwordx4 v17, v[120:123], s[22:23]
	s_add_u32 s22, s22, 0x4000
	s_addc_u32 s23, s23, 0
	s_waitcnt lgkmcnt(4)
	global_store_dwordx4 v17, v[128:131], s[22:23]
	s_add_u32 s22, s22, 0x4000
	s_addc_u32 s23, s23, 0
	s_waitcnt lgkmcnt(3)
	global_store_dwordx4 v17, v[136:139], s[22:23]
	s_add_u32 s22, s22, 0x4000
	s_addc_u32 s23, s23, 0
	s_waitcnt lgkmcnt(2)
	global_store_dwordx4 v17, v[144:147], s[22:23]
	s_add_u32 s22, s22, 0x4000
	s_addc_u32 s23, s23, 0
	s_waitcnt lgkmcnt(1)
	global_store_dwordx4 v17, v[152:155], s[22:23]
	s_add_u32 s22, s22, 0x4000
	s_addc_u32 s23, s23, 0
	s_waitcnt lgkmcnt(0)
	global_store_dwordx4 v17, v[160:163], s[22:23]
	s_addk_i32 s26, 0x1e0
	s_add_i32 s3, s3, 1
	s_cmp_lt_u32 s3, 2
	s_cbranch_scc1 .Lp5w_round
.Lp5w_done:
	s_branch .LBB0_713
	s_lshl_b32 s2, s96, 3
	s_addk_i32 s2, 0xf9e0
	v_add_u32_e32 v0, s2, v209
	s_movk_i32 s2, 0xd00
	v_cmp_gt_u32_e32 vcc, s2, v0
	s_and_saveexec_b64 s[2:3], vcc
	s_cbranch_execz .LBB0_712
	v_add_u32_e32 v17, 0x2100, v0
	v_lshlrev_b32_e32 v0, 8, v236
	v_and_b32_e32 v0, 0x3c000, v0
	v_add_u32_e32 v1, 0, v0
	v_and_b32_e32 v0, 31, v236
	v_lshrrev_b32_e32 v16, 5, v208
	v_lshlrev_b32_e32 v0, 2, v0
	v_mul_u32_u24_e32 v2, 0x84, v16
	v_add3_u32 v18, v1, v0, v2
	v_lshlrev_b32_e32 v2, 3, v236
	v_lshrrev_b32_e32 v19, 3, v208
	v_and_b32_e32 v8, 56, v2
	v_mul_u32_u24_e32 v2, 0x84, v8
	v_lshlrev_b32_e32 v3, 2, v19
	v_readlane_b32 s4, v246, 1
	v_add3_u32 v20, v1, v2, v3
	v_mov_b32_e32 v1, 0
	v_readlane_b32 s12, v246, 9
	v_readlane_b32 s13, v246, 10
	v_lshl_add_u64 v[2:3], s[62:63], 0, v[0:1]
	v_lshl_add_u64 v[4:5], s[66:67], 0, v[0:1]
	v_readlane_b32 s5, v246, 2
	v_lshl_add_u64 v[6:7], s[12:13], 0, v[0:1]
	v_lshlrev_b32_e32 v0, 1, v8
	v_lshl_add_u64 v[12:13], s[74:75], 0, v[0:1]
	s_mov_b64 s[4:5], 0x2300000
	v_lshl_add_u64 v[8:9], v[12:13], 0, s[4:5]
	s_mov_b64 s[4:5], 0x2500000
	v_readlane_b32 s10, v246, 7
	v_readlane_b32 s11, v246, 8
	v_readlane_b32 s14, v246, 11
	v_readlane_b32 s15, v246, 12
	v_readlane_b32 s16, v246, 13
	v_readlane_b32 s17, v246, 14
	v_readlane_b32 s18, v246, 15
	v_readlane_b32 s19, v246, 16
	v_lshl_add_u64 v[10:11], v[12:13], 0, s[4:5]
	s_mov_b64 s[4:5], 0xc00000
	v_or_b32_e32 v21, 8, v19
	v_or_b32_e32 v22, 16, v19
	v_or_b32_e32 v23, 24, v19
	v_lshl_add_u64 v[12:13], v[12:13], 0, s[4:5]
	v_lshlrev_b32_e32 v24, 5, v17
	v_lshlrev_b32_e32 v25, 1, v17
	s_mov_b64 s[4:5], 0
	s_movk_i32 s10, 0x20ff
	s_movk_i32 s11, 0x2bff
	s_movk_i32 s12, 0x60
	s_mov_b32 s13, 0xb000
	s_mov_b32 s14, 0x16000
	s_mov_b32 s15, 0x21000
	s_mov_b32 s16, 0x2c000
	s_mov_b32 s17, 0x37000
	s_mov_b32 s18, 0x42000
	s_mov_b32 s19, 0x4d000
	s_mov_b32 s20, 0x58000
	s_mov_b32 s21, 0x63000
	s_mov_b32 s22, 0x6e000
	s_mov_b32 s23, 0x79000
	s_mov_b32 s24, 0x84000
	s_mov_b32 s25, 0x8f000
	s_mov_b32 s26, 0x9a000
	s_mov_b32 s27, 0xa5000
	s_mov_b32 s28, 0xb0000
	s_mov_b32 s29, 0xbb000
	s_mov_b32 s30, 0xc6000
	s_mov_b32 s31, 0xd1000
	s_mov_b32 s33, 0xdc000
	s_mov_b32 s34, 0xe7000
	s_mov_b32 s35, 0xf2000
	s_mov_b32 s36, 0xfd000
	s_mov_b32 s37, 0x108000
	s_mov_b32 s38, 0x113000
	s_mov_b32 s39, 0x11e000
	s_mov_b32 s40, 0x129000
	s_mov_b32 s41, 0x134000
	s_mov_b32 s42, 0x13f000
	s_mov_b32 s43, 0x14a000
	s_mov_b32 s44, 0x155000
	s_movk_i32 s45, 0x2c1f
	v_add_u32_e32 v26, 0x400, v18
	v_add_u32_e32 v27, 0x800, v18
	v_add_u32_e32 v28, 0xc00, v18
	v_add_u32_e32 v29, 0x1000, v18
	v_add_u32_e32 v30, 0x1400, v18
	v_add_u32_e32 v31, 0x1800, v18
	v_add_u32_e32 v32, 0x1c00, v18
	v_readlane_b32 s6, v246, 3
	v_readlane_b32 s7, v246, 4
	v_readlane_b32 s8, v246, 5
	v_readlane_b32 s9, v246, 6
	s_branch .LBB0_704
